# plus P3: both branch-projection GEMM epilogues rewritten, all 16 (stage 0) / rolling 16 (stage 1) gate+t1 loads in flight instead of one round trip per group
# baseline (speedup 1.0000x reference)
; __device__ __forceinline__ u32x4 pack8(const f32x4 a, const f32x4 b) { u32x4 w; w.x = cvt_pk_bf16(a[0], a[1]); w.y = cvt_pk_bf16(a[2], a[3]); w.z = cvt_pk_bf16(b[0], b[1]); w.w = cvt_pk_bf16(b[2], b[3]); return w; }
; __device__ __forceinline__ void unpack8(const u32x4 w, f32x4& a, f32x4& b) { a = (f32x4){bflo(w.x), bfhi(w.x), bflo(w.y), bfhi(w.y)}; b = (f32x4){bflo(w.z), bfhi(w.z), bflo(w.w), bfhi(w.w)}; }
;     __device__ __forceinline__ void operator()(const f32x4 (&acc)[2][2][4][2], const Unit& u, int wr, int wc, int fr, int fq) const {
;         const int row0 = u.pm * BM + wr * 64 + fr, col0 = u.pn * BM + wc * 32 + 8 * fq;
; #pragma unroll
;         for (int ai = 0; ai < 2; ++ai)
; #pragma unroll
;             for (int m = 0; m < 4; ++m) { const int row = row0 + ai * HALF + m * 16;
; #pragma unroll
;                 for (int bj = 0; bj < 2; ++bj) { const int c = col0 + bj * HALF;
;                     f32x4 g0, g1; unpack8(*(const u32x4*)(gates + (size_t)row * 4096 + STAGE * 2048 + c), g0, g1);
;                     f32x4 v0 = acc[ai][bj][m][0] * g0, v1 = acc[ai][bj][m][1] * g1;
;                     if (STAGE == 0) { *(u32x4*)(t1 + (size_t)row * 2048 + c) = pack8(v0, v1); }
.LBB0_925:
	s_andn2_b64 vcc, exec, s[2:3]
	s_mov_b64 s[2:3], -1
	v_lshl_add_u32 v249, s51, 8, v150
	v_lshl_or_b32 v248, s50, 8, v158
	v_lshlrev_b32_e32 v248, 1, v248
	v_lshl_add_u32 v246, v249, 13, v248
	v_lshl_add_u32 v247, v249, 12, v248
	v_mov_b32_e32 v248, v246
	global_load_dwordx4 v[144:147], v248, s[66:67] offset:0
	global_load_dwordx4 v[166:169], v248, s[66:67] offset:256
	v_add_u32_e32 v248, 0x20000, v246
	global_load_dwordx4 v[170:173], v248, s[66:67] offset:0
	global_load_dwordx4 v[174:177], v248, s[66:67] offset:256
	v_add_u32_e32 v248, 0x40000, v246
	global_load_dwordx4 v[178:181], v248, s[66:67] offset:0
	global_load_dwordx4 v[182:185], v248, s[66:67] offset:256
	v_add_u32_e32 v248, 0x60000, v246
	global_load_dwordx4 v[186:189], v248, s[66:67] offset:0
	global_load_dwordx4 v[190:193], v248, s[66:67] offset:256
	v_add_u32_e32 v248, 0x100000, v246
	global_load_dwordx4 v[200:203], v248, s[66:67] offset:0
	global_load_dwordx4 v[204:207], v248, s[66:67] offset:256
	v_add_u32_e32 v248, 0x120000, v246
	global_load_dwordx4 v[208:211], v248, s[66:67] offset:0
	global_load_dwordx4 v[212:215], v248, s[66:67] offset:256
	v_add_u32_e32 v248, 0x140000, v246
	global_load_dwordx4 v[216:219], v248, s[66:67] offset:0
	global_load_dwordx4 v[220:223], v248, s[66:67] offset:256
	v_add_u32_e32 v248, 0x160000, v246
	global_load_dwordx4 v[224:227], v248, s[66:67] offset:0
	global_load_dwordx4 v[228:231], v248, s[66:67] offset:256
	s_waitcnt vmcnt(15)
	v_lshlrev_b32_e32 v238, 16, v144
	v_and_b32_e32 v239, 0xffff0000, v144
	v_pk_mul_f32 v[126:127], v[126:127], v[238:239]
	v_lshlrev_b32_e32 v240, 16, v145
	v_and_b32_e32 v241, 0xffff0000, v145
	v_pk_mul_f32 v[128:129], v[128:129], v[240:241]
	v_lshlrev_b32_e32 v238, 16, v146
	v_and_b32_e32 v239, 0xffff0000, v146
	v_pk_mul_f32 v[122:123], v[122:123], v[238:239]
	v_lshlrev_b32_e32 v240, 16, v147
	v_and_b32_e32 v241, 0xffff0000, v147
	v_pk_mul_f32 v[124:125], v[124:125], v[240:241]
	v_cvt_pk_bf16_f32 v144, v126, v127
	v_cvt_pk_bf16_f32 v145, v128, v129
	v_cvt_pk_bf16_f32 v146, v122, v123
	v_cvt_pk_bf16_f32 v147, v124, v125
	v_mov_b32_e32 v248, v247
	global_store_dwordx4 v248, v[144:147], s[6:7] offset:0
	s_waitcnt vmcnt(15)
	v_lshlrev_b32_e32 v238, 16, v166
	v_and_b32_e32 v239, 0xffff0000, v166
	v_pk_mul_f32 v[114:115], v[114:115], v[238:239]
	v_lshlrev_b32_e32 v240, 16, v167
	v_and_b32_e32 v241, 0xffff0000, v167
	v_pk_mul_f32 v[116:117], v[116:117], v[240:241]
	v_lshlrev_b32_e32 v238, 16, v168
	v_and_b32_e32 v239, 0xffff0000, v168
	v_pk_mul_f32 v[110:111], v[110:111], v[238:239]
	v_lshlrev_b32_e32 v240, 16, v169
	v_and_b32_e32 v241, 0xffff0000, v169
	v_pk_mul_f32 v[112:113], v[112:113], v[240:241]
	v_cvt_pk_bf16_f32 v166, v114, v115
	v_cvt_pk_bf16_f32 v167, v116, v117
	v_cvt_pk_bf16_f32 v168, v110, v111
	v_cvt_pk_bf16_f32 v169, v112, v113
	global_store_dwordx4 v248, v[166:169], s[6:7] offset:256
	s_waitcnt vmcnt(15)
	v_lshlrev_b32_e32 v238, 16, v170
	v_and_b32_e32 v239, 0xffff0000, v170
	v_pk_mul_f32 v[118:119], v[118:119], v[238:239]
	v_lshlrev_b32_e32 v240, 16, v171
	v_and_b32_e32 v241, 0xffff0000, v171
	v_pk_mul_f32 v[120:121], v[120:121], v[240:241]
	v_lshlrev_b32_e32 v238, 16, v172
	v_and_b32_e32 v239, 0xffff0000, v172
	v_pk_mul_f32 v[106:107], v[106:107], v[238:239]
	v_lshlrev_b32_e32 v240, 16, v173
	v_and_b32_e32 v241, 0xffff0000, v173
	v_pk_mul_f32 v[108:109], v[108:109], v[240:241]
	v_cvt_pk_bf16_f32 v170, v118, v119
	v_cvt_pk_bf16_f32 v171, v120, v121
	v_cvt_pk_bf16_f32 v172, v106, v107
	v_cvt_pk_bf16_f32 v173, v108, v109
	v_add_u32_e32 v248, 0x10000, v247
	global_store_dwordx4 v248, v[170:173], s[6:7] offset:0
	s_waitcnt vmcnt(15)
	v_lshlrev_b32_e32 v238, 16, v174
	v_and_b32_e32 v239, 0xffff0000, v174
	v_pk_mul_f32 v[98:99], v[98:99], v[238:239]
	v_lshlrev_b32_e32 v240, 16, v175
	v_and_b32_e32 v241, 0xffff0000, v175
	v_pk_mul_f32 v[100:101], v[100:101], v[240:241]
	v_lshlrev_b32_e32 v238, 16, v176
	v_and_b32_e32 v239, 0xffff0000, v176
	v_pk_mul_f32 v[94:95], v[94:95], v[238:239]
	v_lshlrev_b32_e32 v240, 16, v177
	v_and_b32_e32 v241, 0xffff0000, v177
	v_pk_mul_f32 v[96:97], v[96:97], v[240:241]
	v_cvt_pk_bf16_f32 v174, v98, v99
	v_cvt_pk_bf16_f32 v175, v100, v101
	v_cvt_pk_bf16_f32 v176, v94, v95
	v_cvt_pk_bf16_f32 v177, v96, v97
	global_store_dwordx4 v248, v[174:177], s[6:7] offset:256
	s_waitcnt vmcnt(15)
	v_lshlrev_b32_e32 v238, 16, v178
	v_and_b32_e32 v239, 0xffff0000, v178
	v_pk_mul_f32 v[102:103], v[102:103], v[238:239]
	v_lshlrev_b32_e32 v240, 16, v179
	v_and_b32_e32 v241, 0xffff0000, v179
	v_pk_mul_f32 v[104:105], v[104:105], v[240:241]
	v_lshlrev_b32_e32 v238, 16, v180
	v_and_b32_e32 v239, 0xffff0000, v180
	v_pk_mul_f32 v[90:91], v[90:91], v[238:239]
	v_lshlrev_b32_e32 v240, 16, v181
	v_and_b32_e32 v241, 0xffff0000, v181
	v_pk_mul_f32 v[92:93], v[92:93], v[240:241]
	v_cvt_pk_bf16_f32 v178, v102, v103
	v_cvt_pk_bf16_f32 v179, v104, v105
	v_cvt_pk_bf16_f32 v180, v90, v91
	v_cvt_pk_bf16_f32 v181, v92, v93
	v_add_u32_e32 v248, 0x20000, v247
	global_store_dwordx4 v248, v[178:181], s[6:7] offset:0
	s_waitcnt vmcnt(15)
	v_lshlrev_b32_e32 v238, 16, v182
	v_and_b32_e32 v239, 0xffff0000, v182
	v_pk_mul_f32 v[82:83], v[82:83], v[238:239]
	v_lshlrev_b32_e32 v240, 16, v183
	v_and_b32_e32 v241, 0xffff0000, v183
	v_pk_mul_f32 v[84:85], v[84:85], v[240:241]
	v_lshlrev_b32_e32 v238, 16, v184
	v_and_b32_e32 v239, 0xffff0000, v184
	v_pk_mul_f32 v[78:79], v[78:79], v[238:239]
	v_lshlrev_b32_e32 v240, 16, v185
	v_and_b32_e32 v241, 0xffff0000, v185
	v_pk_mul_f32 v[80:81], v[80:81], v[240:241]
	v_cvt_pk_bf16_f32 v182, v82, v83
	v_cvt_pk_bf16_f32 v183, v84, v85
	v_cvt_pk_bf16_f32 v184, v78, v79
	v_cvt_pk_bf16_f32 v185, v80, v81
	global_store_dwordx4 v248, v[182:185], s[6:7] offset:256
	s_waitcnt vmcnt(15)
; __device__ __forceinline__ u32x4 pack8(const f32x4 a, const f32x4 b) { u32x4 w; w.x = cvt_pk_bf16(a[0], a[1]); w.y = cvt_pk_bf16(a[2], a[3]); w.z = cvt_pk_bf16(b[0], b[1]); w.w = cvt_pk_bf16(b[2], b[3]); return w; }
; __device__ __forceinline__ void unpack8(const u32x4 w, f32x4& a, f32x4& b) { a = (f32x4){bflo(w.x), bfhi(w.x), bflo(w.y), bfhi(w.y)}; b = (f32x4){bflo(w.z), bfhi(w.z), bflo(w.w), bfhi(w.w)}; }
;     __device__ __forceinline__ void operator()(const f32x4 (&acc)[2][2][4][2], const Unit& u, int wr, int wc, int fr, int fq) const {
;         const int row0 = u.pm * BM + wr * 64 + fr, col0 = u.pn * BM + wc * 32 + 8 * fq;
; #pragma unroll
;         for (int ai = 0; ai < 2; ++ai)
; #pragma unroll
;             for (int m = 0; m < 4; ++m) { const int row = row0 + ai * HALF + m * 16;
; #pragma unroll
;                 for (int bj = 0; bj < 2; ++bj) { const int c = col0 + bj * HALF;
;                     f32x4 g0, g1; unpack8(*(const u32x4*)(gates + (size_t)row * 4096 + STAGE * 2048 + c), g0, g1);
;                     f32x4 v0 = acc[ai][bj][m][0] * g0, v1 = acc[ai][bj][m][1] * g1;
;                     if (STAGE == 0) { *(u32x4*)(t1 + (size_t)row * 2048 + c) = pack8(v0, v1); }
	v_lshlrev_b32_e32 v238, 16, v186
	v_and_b32_e32 v239, 0xffff0000, v186
	v_pk_mul_f32 v[86:87], v[86:87], v[238:239]
	v_lshlrev_b32_e32 v240, 16, v187
	v_and_b32_e32 v241, 0xffff0000, v187
	v_pk_mul_f32 v[88:89], v[88:89], v[240:241]
	v_lshlrev_b32_e32 v238, 16, v188
	v_and_b32_e32 v239, 0xffff0000, v188
	v_pk_mul_f32 v[74:75], v[74:75], v[238:239]
	v_lshlrev_b32_e32 v240, 16, v189
	v_and_b32_e32 v241, 0xffff0000, v189
	v_pk_mul_f32 v[76:77], v[76:77], v[240:241]
	v_cvt_pk_bf16_f32 v186, v86, v87
	v_cvt_pk_bf16_f32 v187, v88, v89
	v_cvt_pk_bf16_f32 v188, v74, v75
	v_cvt_pk_bf16_f32 v189, v76, v77
	v_add_u32_e32 v248, 0x30000, v247
	global_store_dwordx4 v248, v[186:189], s[6:7] offset:0
	s_waitcnt vmcnt(15)
	v_lshlrev_b32_e32 v238, 16, v190
	v_and_b32_e32 v239, 0xffff0000, v190
	v_pk_mul_f32 v[70:71], v[70:71], v[238:239]
	v_lshlrev_b32_e32 v240, 16, v191
	v_and_b32_e32 v241, 0xffff0000, v191
	v_pk_mul_f32 v[72:73], v[72:73], v[240:241]
	v_lshlrev_b32_e32 v238, 16, v192
	v_and_b32_e32 v239, 0xffff0000, v192
	v_pk_mul_f32 v[66:67], v[66:67], v[238:239]
	v_lshlrev_b32_e32 v240, 16, v193
	v_and_b32_e32 v241, 0xffff0000, v193
	v_pk_mul_f32 v[68:69], v[68:69], v[240:241]
	v_cvt_pk_bf16_f32 v190, v70, v71
	v_cvt_pk_bf16_f32 v191, v72, v73
	v_cvt_pk_bf16_f32 v192, v66, v67
	v_cvt_pk_bf16_f32 v193, v68, v69
	global_store_dwordx4 v248, v[190:193], s[6:7] offset:256
	s_waitcnt vmcnt(15)
	v_lshlrev_b32_e32 v238, 16, v200
	v_and_b32_e32 v239, 0xffff0000, v200
	v_pk_mul_f32 v[62:63], v[62:63], v[238:239]
	v_lshlrev_b32_e32 v240, 16, v201
	v_and_b32_e32 v241, 0xffff0000, v201
	v_pk_mul_f32 v[64:65], v[64:65], v[240:241]
	v_lshlrev_b32_e32 v238, 16, v202
	v_and_b32_e32 v239, 0xffff0000, v202
	v_pk_mul_f32 v[58:59], v[58:59], v[238:239]
	v_lshlrev_b32_e32 v240, 16, v203
	v_and_b32_e32 v241, 0xffff0000, v203
	v_pk_mul_f32 v[60:61], v[60:61], v[240:241]
	v_cvt_pk_bf16_f32 v200, v62, v63
	v_cvt_pk_bf16_f32 v201, v64, v65
	v_cvt_pk_bf16_f32 v202, v58, v59
	v_cvt_pk_bf16_f32 v203, v60, v61
	v_add_u32_e32 v248, 0x80000, v247
	global_store_dwordx4 v248, v[200:203], s[6:7] offset:0
	s_waitcnt vmcnt(15)
	v_lshlrev_b32_e32 v238, 16, v204
	v_and_b32_e32 v239, 0xffff0000, v204
	v_pk_mul_f32 v[50:51], v[50:51], v[238:239]
	v_lshlrev_b32_e32 v240, 16, v205
	v_and_b32_e32 v241, 0xffff0000, v205
	v_pk_mul_f32 v[52:53], v[52:53], v[240:241]
	v_lshlrev_b32_e32 v238, 16, v206
	v_and_b32_e32 v239, 0xffff0000, v206
	v_pk_mul_f32 v[46:47], v[46:47], v[238:239]
	v_lshlrev_b32_e32 v240, 16, v207
	v_and_b32_e32 v241, 0xffff0000, v207
	v_pk_mul_f32 v[48:49], v[48:49], v[240:241]
	v_cvt_pk_bf16_f32 v204, v50, v51
	v_cvt_pk_bf16_f32 v205, v52, v53
	v_cvt_pk_bf16_f32 v206, v46, v47
	v_cvt_pk_bf16_f32 v207, v48, v49
	global_store_dwordx4 v248, v[204:207], s[6:7] offset:256
	s_waitcnt vmcnt(15)
	v_lshlrev_b32_e32 v238, 16, v208
	v_and_b32_e32 v239, 0xffff0000, v208
	v_pk_mul_f32 v[54:55], v[54:55], v[238:239]
	v_lshlrev_b32_e32 v240, 16, v209
	v_and_b32_e32 v241, 0xffff0000, v209
	v_pk_mul_f32 v[56:57], v[56:57], v[240:241]
	v_lshlrev_b32_e32 v238, 16, v210
	v_and_b32_e32 v239, 0xffff0000, v210
	v_pk_mul_f32 v[42:43], v[42:43], v[238:239]
	v_lshlrev_b32_e32 v240, 16, v211
	v_and_b32_e32 v241, 0xffff0000, v211
	v_pk_mul_f32 v[44:45], v[44:45], v[240:241]
	v_cvt_pk_bf16_f32 v208, v54, v55
	v_cvt_pk_bf16_f32 v209, v56, v57
	v_cvt_pk_bf16_f32 v210, v42, v43
	v_cvt_pk_bf16_f32 v211, v44, v45
	v_add_u32_e32 v248, 0x90000, v247
	global_store_dwordx4 v248, v[208:211], s[6:7] offset:0
	s_waitcnt vmcnt(15)
	v_lshlrev_b32_e32 v238, 16, v212
	v_and_b32_e32 v239, 0xffff0000, v212
	v_pk_mul_f32 v[34:35], v[34:35], v[238:239]
	v_lshlrev_b32_e32 v240, 16, v213
	v_and_b32_e32 v241, 0xffff0000, v213
	v_pk_mul_f32 v[36:37], v[36:37], v[240:241]
	v_lshlrev_b32_e32 v238, 16, v214
	v_and_b32_e32 v239, 0xffff0000, v214
	v_pk_mul_f32 v[30:31], v[30:31], v[238:239]
	v_lshlrev_b32_e32 v240, 16, v215
	v_and_b32_e32 v241, 0xffff0000, v215
	v_pk_mul_f32 v[32:33], v[32:33], v[240:241]
	v_cvt_pk_bf16_f32 v212, v34, v35
	v_cvt_pk_bf16_f32 v213, v36, v37
	v_cvt_pk_bf16_f32 v214, v30, v31
	v_cvt_pk_bf16_f32 v215, v32, v33
	global_store_dwordx4 v248, v[212:215], s[6:7] offset:256
	s_waitcnt vmcnt(15)
	v_lshlrev_b32_e32 v238, 16, v216
	v_and_b32_e32 v239, 0xffff0000, v216
	v_pk_mul_f32 v[38:39], v[38:39], v[238:239]
	v_lshlrev_b32_e32 v240, 16, v217
	v_and_b32_e32 v241, 0xffff0000, v217
	v_pk_mul_f32 v[40:41], v[40:41], v[240:241]
	v_lshlrev_b32_e32 v238, 16, v218
	v_and_b32_e32 v239, 0xffff0000, v218
	v_pk_mul_f32 v[26:27], v[26:27], v[238:239]
	v_lshlrev_b32_e32 v240, 16, v219
	v_and_b32_e32 v241, 0xffff0000, v219
	v_pk_mul_f32 v[28:29], v[28:29], v[240:241]
	v_cvt_pk_bf16_f32 v216, v38, v39
	v_cvt_pk_bf16_f32 v217, v40, v41
	v_cvt_pk_bf16_f32 v218, v26, v27
	v_cvt_pk_bf16_f32 v219, v28, v29
	v_add_u32_e32 v248, 0xa0000, v247
	global_store_dwordx4 v248, v[216:219], s[6:7] offset:0
	s_waitcnt vmcnt(15)
	v_lshlrev_b32_e32 v238, 16, v220
	v_and_b32_e32 v239, 0xffff0000, v220
	v_pk_mul_f32 v[18:19], v[18:19], v[238:239]
	v_lshlrev_b32_e32 v240, 16, v221
	v_and_b32_e32 v241, 0xffff0000, v221
	v_pk_mul_f32 v[20:21], v[20:21], v[240:241]
	v_lshlrev_b32_e32 v238, 16, v222
	v_and_b32_e32 v239, 0xffff0000, v222
	v_pk_mul_f32 v[14:15], v[14:15], v[238:239]
	v_lshlrev_b32_e32 v240, 16, v223
	v_and_b32_e32 v241, 0xffff0000, v223
	v_pk_mul_f32 v[16:17], v[16:17], v[240:241]
	v_cvt_pk_bf16_f32 v220, v18, v19
	v_cvt_pk_bf16_f32 v221, v20, v21
	v_cvt_pk_bf16_f32 v222, v14, v15
	v_cvt_pk_bf16_f32 v223, v16, v17
	global_store_dwordx4 v248, v[220:223], s[6:7] offset:256
	s_waitcnt vmcnt(15)
	v_lshlrev_b32_e32 v238, 16, v224
	v_and_b32_e32 v239, 0xffff0000, v224
	v_pk_mul_f32 v[22:23], v[22:23], v[238:239]
	v_lshlrev_b32_e32 v240, 16, v225
	v_and_b32_e32 v241, 0xffff0000, v225
	v_pk_mul_f32 v[24:25], v[24:25], v[240:241]
	v_lshlrev_b32_e32 v238, 16, v226
	v_and_b32_e32 v239, 0xffff0000, v226
	v_pk_mul_f32 v[10:11], v[10:11], v[238:239]
	v_lshlrev_b32_e32 v240, 16, v227
	v_and_b32_e32 v241, 0xffff0000, v227
	v_pk_mul_f32 v[12:13], v[12:13], v[240:241]
	v_cvt_pk_bf16_f32 v224, v22, v23
	v_cvt_pk_bf16_f32 v225, v24, v25
	v_cvt_pk_bf16_f32 v226, v10, v11
	v_cvt_pk_bf16_f32 v227, v12, v13
	v_add_u32_e32 v248, 0xb0000, v247
	global_store_dwordx4 v248, v[224:227], s[6:7] offset:0
	s_waitcnt vmcnt(15)
	v_lshlrev_b32_e32 v238, 16, v228
	v_and_b32_e32 v239, 0xffff0000, v228
	v_pk_mul_f32 v[6:7], v[6:7], v[238:239]
	v_lshlrev_b32_e32 v240, 16, v229
	v_and_b32_e32 v241, 0xffff0000, v229
	v_pk_mul_f32 v[8:9], v[8:9], v[240:241]
	v_lshlrev_b32_e32 v238, 16, v230
	v_and_b32_e32 v239, 0xffff0000, v230
	v_pk_mul_f32 v[2:3], v[2:3], v[238:239]
	v_lshlrev_b32_e32 v240, 16, v231
	v_and_b32_e32 v241, 0xffff0000, v231
	v_pk_mul_f32 v[4:5], v[4:5], v[240:241]
	v_cvt_pk_bf16_f32 v228, v6, v7
	v_cvt_pk_bf16_f32 v229, v8, v9
	v_cvt_pk_bf16_f32 v230, v2, v3
	v_cvt_pk_bf16_f32 v231, v4, v5
	global_store_dwordx4 v248, v[228:231], s[6:7] offset:256
	s_cbranch_vccnz .LBB0_920
; #define PG8_BAR __builtin_amdgcn_s_barrier()
; template <class Epi, class Sched, bool ALIGN_EPI = false, bool SP2 = false>
; __device__ __forceinline__ void gemm_phase(PG8_LAS unsigned char* lds, const Gemm g, const Sched& S, const Epi& E) {
;     ...
;         if constexpr (ALIGN_EPI) { if (wr == 0) PG8_BAR; }
;         if constexpr (!Epi::AFTER_DRAIN) { E(acc, cur, wr, wc, fr, fq); S.done(cur); }
;         if (!has_next) break;
; #pragma unroll
;         for (int a = 0; a < 2; ++a)
; #pragma unroll
;             for (int b = 0; b < 2; ++b)
; #pragma unroll
;                 for (int m = 0; m < 4; ++m)
; #pragma unroll
;                     for (int n = 0; n < 2; ++n) acc[a][b][m][n] = (f32x4){0.f, 0.f, 0.f, 0.f};
;         cur = nxt; cA = nA; cB = nB; ++ui;
;         if constexpr (ALIGN_EPI) { if (wr == 1) PG8_BAR; }
	s_andn2_b64 vcc, exec, s[12:13]
	s_cbranch_vccnz .LBB0_919
	s_barrier
	s_branch .LBB0_919

; __device__ __forceinline__ u32x4 pack8(const f32x4 a, const f32x4 b) { u32x4 w; w.x = cvt_pk_bf16(a[0], a[1]); w.y = cvt_pk_bf16(a[2], a[3]); w.z = cvt_pk_bf16(b[0], b[1]); w.w = cvt_pk_bf16(b[2], b[3]); return w; }
; __device__ __forceinline__ void unpack8(const u32x4 w, f32x4& a, f32x4& b) { a = (f32x4){bflo(w.x), bfhi(w.x), bflo(w.y), bfhi(w.y)}; b = (f32x4){bflo(w.z), bfhi(w.z), bflo(w.w), bfhi(w.w)}; }
;     __device__ __forceinline__ void operator()(const f32x4 (&acc)[2][2][4][2], const Unit& u, int wr, int wc, int fr, int fq) const {
;         const int row0 = u.pm * BM + wr * 64 + fr, col0 = u.pn * BM + wc * 32 + 8 * fq;
; #pragma unroll
;         for (int ai = 0; ai < 2; ++ai)
; #pragma unroll
;             for (int m = 0; m < 4; ++m) { const int row = row0 + ai * HALF + m * 16;
; #pragma unroll
;                 for (int bj = 0; bj < 2; ++bj) { const int c = col0 + bj * HALF;
;                     f32x4 g0, g1; unpack8(*(const u32x4*)(gates + (size_t)row * 4096 + STAGE * 2048 + c), g0, g1);
;                     f32x4 v0 = acc[ai][bj][m][0] * g0, v1 = acc[ai][bj][m][1] * g1;
;                     if (STAGE == 0) { *(u32x4*)(t1 + (size_t)row * 2048 + c) = pack8(v0, v1); }
;                     else { f32x4 t0, t1v; unpack8(*(const u32x4*)(t1 + (size_t)row * 2048 + c), t0, t1v); *(u32x4*)(g + (size_t)row * 2048 + c) = pack8(v0 + t0, v1 + t1v); } } }
.LBB0_939:
	s_andn2_b64 vcc, exec, s[2:3]
	s_mov_b64 s[2:3], -1
	v_lshl_add_u32 v249, s52, 8, v150
	v_lshl_or_b32 v248, s51, 8, v152
	v_lshlrev_b32_e32 v248, 1, v248
	v_lshl_add_u32 v246, v249, 13, v248
	v_add_u32_e32 v246, 0x1000, v246
	v_lshl_add_u32 v247, v249, 12, v248
	v_mov_b32_e32 v248, v246
	global_load_dwordx4 v[144:147], v248, s[66:67] offset:0
	v_mov_b32_e32 v248, v247
	global_load_dwordx4 v[156:159], v248, s[6:7] offset:0
	v_mov_b32_e32 v248, v246
	global_load_dwordx4 v[160:163], v248, s[66:67] offset:256
	v_mov_b32_e32 v248, v247
	global_load_dwordx4 v[166:169], v248, s[6:7] offset:256
	v_add_u32_e32 v248, 0x20000, v246
	global_load_dwordx4 v[170:173], v248, s[66:67] offset:0
	v_add_u32_e32 v248, 0x10000, v247
	global_load_dwordx4 v[174:177], v248, s[6:7] offset:0
	v_add_u32_e32 v248, 0x20000, v246
	global_load_dwordx4 v[178:181], v248, s[66:67] offset:256
	v_add_u32_e32 v248, 0x10000, v247
	global_load_dwordx4 v[182:185], v248, s[6:7] offset:256
	v_add_u32_e32 v248, 0x40000, v246
	global_load_dwordx4 v[186:189], v248, s[66:67] offset:0
	v_add_u32_e32 v248, 0x20000, v247
	global_load_dwordx4 v[190:193], v248, s[6:7] offset:0
	v_add_u32_e32 v248, 0x40000, v246
	global_load_dwordx4 v[200:203], v248, s[66:67] offset:256
	v_add_u32_e32 v248, 0x20000, v247
	global_load_dwordx4 v[204:207], v248, s[6:7] offset:256
	v_add_u32_e32 v248, 0x60000, v246
	global_load_dwordx4 v[208:211], v248, s[66:67] offset:0
	v_add_u32_e32 v248, 0x30000, v247
	global_load_dwordx4 v[212:215], v248, s[6:7] offset:0
	v_add_u32_e32 v248, 0x60000, v246
	global_load_dwordx4 v[216:219], v248, s[66:67] offset:256
	v_add_u32_e32 v248, 0x30000, v247
	global_load_dwordx4 v[220:223], v248, s[6:7] offset:256
	s_waitcnt vmcnt(14)
	v_lshlrev_b32_e32 v238, 16, v144
	v_and_b32_e32 v239, 0xffff0000, v144
	v_lshlrev_b32_e32 v242, 16, v156
	v_and_b32_e32 v243, 0xffff0000, v156
	v_pk_fma_f32 v[126:127], v[126:127], v[238:239], v[242:243]
	v_lshlrev_b32_e32 v240, 16, v145
	v_and_b32_e32 v241, 0xffff0000, v145
	v_lshlrev_b32_e32 v244, 16, v157
	v_and_b32_e32 v245, 0xffff0000, v157
	v_pk_fma_f32 v[128:129], v[128:129], v[240:241], v[244:245]
	v_lshlrev_b32_e32 v238, 16, v146
	v_and_b32_e32 v239, 0xffff0000, v146
	v_lshlrev_b32_e32 v242, 16, v158
	v_and_b32_e32 v243, 0xffff0000, v158
	v_pk_fma_f32 v[122:123], v[122:123], v[238:239], v[242:243]
	v_lshlrev_b32_e32 v240, 16, v147
	v_and_b32_e32 v241, 0xffff0000, v147
	v_lshlrev_b32_e32 v244, 16, v159
	v_and_b32_e32 v245, 0xffff0000, v159
	v_pk_fma_f32 v[124:125], v[124:125], v[240:241], v[244:245]
	v_cvt_pk_bf16_f32 v144, v126, v127
	v_cvt_pk_bf16_f32 v145, v128, v129
	v_cvt_pk_bf16_f32 v146, v122, v123
	v_cvt_pk_bf16_f32 v147, v124, v125
	v_mov_b32_e32 v248, v247
	global_store_dwordx4 v248, v[144:147], s[0:1] offset:0
	v_add_u32_e32 v248, 0x80000, v247
	global_load_dwordx4 v[156:159], v248, s[6:7] offset:0
	v_add_u32_e32 v248, 0x100000, v246
	global_load_dwordx4 v[144:147], v248, s[66:67] offset:0
	s_waitcnt vmcnt(15)
	v_lshlrev_b32_e32 v238, 16, v160
	v_and_b32_e32 v239, 0xffff0000, v160
	v_lshlrev_b32_e32 v242, 16, v166
	v_and_b32_e32 v243, 0xffff0000, v166
	v_pk_fma_f32 v[118:119], v[118:119], v[238:239], v[242:243]
	v_lshlrev_b32_e32 v240, 16, v161
	v_and_b32_e32 v241, 0xffff0000, v161
	v_lshlrev_b32_e32 v244, 16, v167
	v_and_b32_e32 v245, 0xffff0000, v167
	v_pk_fma_f32 v[120:121], v[120:121], v[240:241], v[244:245]
	v_lshlrev_b32_e32 v238, 16, v162
	v_and_b32_e32 v239, 0xffff0000, v162
	v_lshlrev_b32_e32 v242, 16, v168
	v_and_b32_e32 v243, 0xffff0000, v168
	v_pk_fma_f32 v[114:115], v[114:115], v[238:239], v[242:243]
	v_lshlrev_b32_e32 v240, 16, v163
	v_and_b32_e32 v241, 0xffff0000, v163
	v_lshlrev_b32_e32 v244, 16, v169
	v_and_b32_e32 v245, 0xffff0000, v169
	v_pk_fma_f32 v[116:117], v[116:117], v[240:241], v[244:245]
	v_cvt_pk_bf16_f32 v160, v118, v119
	v_cvt_pk_bf16_f32 v161, v120, v121
	v_cvt_pk_bf16_f32 v162, v114, v115
	v_cvt_pk_bf16_f32 v163, v116, v117
	v_mov_b32_e32 v248, v247
	global_store_dwordx4 v248, v[160:163], s[0:1] offset:256
	v_add_u32_e32 v248, 0x80000, v247
	global_load_dwordx4 v[166:169], v248, s[6:7] offset:256
	v_add_u32_e32 v248, 0x100000, v246
	global_load_dwordx4 v[160:163], v248, s[66:67] offset:256
	s_waitcnt vmcnt(16)
	v_lshlrev_b32_e32 v238, 16, v170
	v_and_b32_e32 v239, 0xffff0000, v170
	v_lshlrev_b32_e32 v242, 16, v174
	v_and_b32_e32 v243, 0xffff0000, v174
	v_pk_fma_f32 v[110:111], v[110:111], v[238:239], v[242:243]
	v_lshlrev_b32_e32 v240, 16, v171
	v_and_b32_e32 v241, 0xffff0000, v171
	v_lshlrev_b32_e32 v244, 16, v175
	v_and_b32_e32 v245, 0xffff0000, v175
	v_pk_fma_f32 v[112:113], v[112:113], v[240:241], v[244:245]
	v_lshlrev_b32_e32 v238, 16, v172
	v_and_b32_e32 v239, 0xffff0000, v172
	v_lshlrev_b32_e32 v242, 16, v176
	v_and_b32_e32 v243, 0xffff0000, v176
	v_pk_fma_f32 v[106:107], v[106:107], v[238:239], v[242:243]
	v_lshlrev_b32_e32 v240, 16, v173
	v_and_b32_e32 v241, 0xffff0000, v173
	v_lshlrev_b32_e32 v244, 16, v177
	v_and_b32_e32 v245, 0xffff0000, v177
	v_pk_fma_f32 v[108:109], v[108:109], v[240:241], v[244:245]
	v_cvt_pk_bf16_f32 v170, v110, v111
	v_cvt_pk_bf16_f32 v171, v112, v113
	v_cvt_pk_bf16_f32 v172, v106, v107
	v_cvt_pk_bf16_f32 v173, v108, v109
	v_add_u32_e32 v248, 0x10000, v247
	global_store_dwordx4 v248, v[170:173], s[0:1] offset:0
	v_add_u32_e32 v248, 0x90000, v247
	global_load_dwordx4 v[174:177], v248, s[6:7] offset:0
	v_add_u32_e32 v248, 0x120000, v246
	global_load_dwordx4 v[170:173], v248, s[66:67] offset:0
	s_waitcnt vmcnt(17)
; __device__ __forceinline__ u32x4 pack8(const f32x4 a, const f32x4 b) { u32x4 w; w.x = cvt_pk_bf16(a[0], a[1]); w.y = cvt_pk_bf16(a[2], a[3]); w.z = cvt_pk_bf16(b[0], b[1]); w.w = cvt_pk_bf16(b[2], b[3]); return w; }
; __device__ __forceinline__ void unpack8(const u32x4 w, f32x4& a, f32x4& b) { a = (f32x4){bflo(w.x), bfhi(w.x), bflo(w.y), bfhi(w.y)}; b = (f32x4){bflo(w.z), bfhi(w.z), bflo(w.w), bfhi(w.w)}; }
;     __device__ __forceinline__ void operator()(const f32x4 (&acc)[2][2][4][2], const Unit& u, int wr, int wc, int fr, int fq) const {
;         const int row0 = u.pm * BM + wr * 64 + fr, col0 = u.pn * BM + wc * 32 + 8 * fq;
; #pragma unroll
;         for (int ai = 0; ai < 2; ++ai)
; #pragma unroll
;             for (int m = 0; m < 4; ++m) { const int row = row0 + ai * HALF + m * 16;
; #pragma unroll
;                 for (int bj = 0; bj < 2; ++bj) { const int c = col0 + bj * HALF;
;                     f32x4 g0, g1; unpack8(*(const u32x4*)(gates + (size_t)row * 4096 + STAGE * 2048 + c), g0, g1);
;                     f32x4 v0 = acc[ai][bj][m][0] * g0, v1 = acc[ai][bj][m][1] * g1;
;                     if (STAGE == 0) { *(u32x4*)(t1 + (size_t)row * 2048 + c) = pack8(v0, v1); }
;                     else { f32x4 t0, t1v; unpack8(*(const u32x4*)(t1 + (size_t)row * 2048 + c), t0, t1v); *(u32x4*)(g + (size_t)row * 2048 + c) = pack8(v0 + t0, v1 + t1v); } } }
	v_lshlrev_b32_e32 v238, 16, v178
	v_and_b32_e32 v239, 0xffff0000, v178
	v_lshlrev_b32_e32 v242, 16, v182
	v_and_b32_e32 v243, 0xffff0000, v182
	v_pk_fma_f32 v[102:103], v[102:103], v[238:239], v[242:243]
	v_lshlrev_b32_e32 v240, 16, v179
	v_and_b32_e32 v241, 0xffff0000, v179
	v_lshlrev_b32_e32 v244, 16, v183
	v_and_b32_e32 v245, 0xffff0000, v183
	v_pk_fma_f32 v[104:105], v[104:105], v[240:241], v[244:245]
	v_lshlrev_b32_e32 v238, 16, v180
	v_and_b32_e32 v239, 0xffff0000, v180
	v_lshlrev_b32_e32 v242, 16, v184
	v_and_b32_e32 v243, 0xffff0000, v184
	v_pk_fma_f32 v[98:99], v[98:99], v[238:239], v[242:243]
	v_lshlrev_b32_e32 v240, 16, v181
	v_and_b32_e32 v241, 0xffff0000, v181
	v_lshlrev_b32_e32 v244, 16, v185
	v_and_b32_e32 v245, 0xffff0000, v185
	v_pk_fma_f32 v[100:101], v[100:101], v[240:241], v[244:245]
	v_cvt_pk_bf16_f32 v178, v102, v103
	v_cvt_pk_bf16_f32 v179, v104, v105
	v_cvt_pk_bf16_f32 v180, v98, v99
	v_cvt_pk_bf16_f32 v181, v100, v101
	v_add_u32_e32 v248, 0x10000, v247
	global_store_dwordx4 v248, v[178:181], s[0:1] offset:256
	v_add_u32_e32 v248, 0x90000, v247
	global_load_dwordx4 v[182:185], v248, s[6:7] offset:256
	v_add_u32_e32 v248, 0x120000, v246
	global_load_dwordx4 v[178:181], v248, s[66:67] offset:256
	s_waitcnt vmcnt(18)
	v_lshlrev_b32_e32 v238, 16, v186
	v_and_b32_e32 v239, 0xffff0000, v186
	v_lshlrev_b32_e32 v242, 16, v190
	v_and_b32_e32 v243, 0xffff0000, v190
	v_pk_fma_f32 v[94:95], v[94:95], v[238:239], v[242:243]
	v_lshlrev_b32_e32 v240, 16, v187
	v_and_b32_e32 v241, 0xffff0000, v187
	v_lshlrev_b32_e32 v244, 16, v191
	v_and_b32_e32 v245, 0xffff0000, v191
	v_pk_fma_f32 v[96:97], v[96:97], v[240:241], v[244:245]
	v_lshlrev_b32_e32 v238, 16, v188
	v_and_b32_e32 v239, 0xffff0000, v188
	v_lshlrev_b32_e32 v242, 16, v192
	v_and_b32_e32 v243, 0xffff0000, v192
	v_pk_fma_f32 v[90:91], v[90:91], v[238:239], v[242:243]
	v_lshlrev_b32_e32 v240, 16, v189
	v_and_b32_e32 v241, 0xffff0000, v189
	v_lshlrev_b32_e32 v244, 16, v193
	v_and_b32_e32 v245, 0xffff0000, v193
	v_pk_fma_f32 v[92:93], v[92:93], v[240:241], v[244:245]
	v_cvt_pk_bf16_f32 v186, v94, v95
	v_cvt_pk_bf16_f32 v187, v96, v97
	v_cvt_pk_bf16_f32 v188, v90, v91
	v_cvt_pk_bf16_f32 v189, v92, v93
	v_add_u32_e32 v248, 0x20000, v247
	global_store_dwordx4 v248, v[186:189], s[0:1] offset:0
	v_add_u32_e32 v248, 0xa0000, v247
	global_load_dwordx4 v[190:193], v248, s[6:7] offset:0
	v_add_u32_e32 v248, 0x140000, v246
	global_load_dwordx4 v[186:189], v248, s[66:67] offset:0
	s_waitcnt vmcnt(19)
	v_lshlrev_b32_e32 v238, 16, v200
	v_and_b32_e32 v239, 0xffff0000, v200
	v_lshlrev_b32_e32 v242, 16, v204
	v_and_b32_e32 v243, 0xffff0000, v204
	v_pk_fma_f32 v[86:87], v[86:87], v[238:239], v[242:243]
	v_lshlrev_b32_e32 v240, 16, v201
	v_and_b32_e32 v241, 0xffff0000, v201
	v_lshlrev_b32_e32 v244, 16, v205
	v_and_b32_e32 v245, 0xffff0000, v205
	v_pk_fma_f32 v[88:89], v[88:89], v[240:241], v[244:245]
	v_lshlrev_b32_e32 v238, 16, v202
	v_and_b32_e32 v239, 0xffff0000, v202
	v_lshlrev_b32_e32 v242, 16, v206
	v_and_b32_e32 v243, 0xffff0000, v206
	v_pk_fma_f32 v[82:83], v[82:83], v[238:239], v[242:243]
	v_lshlrev_b32_e32 v240, 16, v203
	v_and_b32_e32 v241, 0xffff0000, v203
	v_lshlrev_b32_e32 v244, 16, v207
	v_and_b32_e32 v245, 0xffff0000, v207
	v_pk_fma_f32 v[84:85], v[84:85], v[240:241], v[244:245]
	v_cvt_pk_bf16_f32 v200, v86, v87
	v_cvt_pk_bf16_f32 v201, v88, v89
	v_cvt_pk_bf16_f32 v202, v82, v83
	v_cvt_pk_bf16_f32 v203, v84, v85
	v_add_u32_e32 v248, 0x20000, v247
	global_store_dwordx4 v248, v[200:203], s[0:1] offset:256
	v_add_u32_e32 v248, 0xa0000, v247
	global_load_dwordx4 v[204:207], v248, s[6:7] offset:256
	v_add_u32_e32 v248, 0x140000, v246
	global_load_dwordx4 v[200:203], v248, s[66:67] offset:256
	s_waitcnt vmcnt(20)
	v_lshlrev_b32_e32 v238, 16, v208
	v_and_b32_e32 v239, 0xffff0000, v208
	v_lshlrev_b32_e32 v242, 16, v212
	v_and_b32_e32 v243, 0xffff0000, v212
	v_pk_fma_f32 v[78:79], v[78:79], v[238:239], v[242:243]
	v_lshlrev_b32_e32 v240, 16, v209
	v_and_b32_e32 v241, 0xffff0000, v209
	v_lshlrev_b32_e32 v244, 16, v213
	v_and_b32_e32 v245, 0xffff0000, v213
	v_pk_fma_f32 v[80:81], v[80:81], v[240:241], v[244:245]
	v_lshlrev_b32_e32 v238, 16, v210
	v_and_b32_e32 v239, 0xffff0000, v210
	v_lshlrev_b32_e32 v242, 16, v214
	v_and_b32_e32 v243, 0xffff0000, v214
	v_pk_fma_f32 v[74:75], v[74:75], v[238:239], v[242:243]
	v_lshlrev_b32_e32 v240, 16, v211
	v_and_b32_e32 v241, 0xffff0000, v211
	v_lshlrev_b32_e32 v244, 16, v215
	v_and_b32_e32 v245, 0xffff0000, v215
	v_pk_fma_f32 v[76:77], v[76:77], v[240:241], v[244:245]
	v_cvt_pk_bf16_f32 v208, v78, v79
	v_cvt_pk_bf16_f32 v209, v80, v81
	v_cvt_pk_bf16_f32 v210, v74, v75
	v_cvt_pk_bf16_f32 v211, v76, v77
	v_add_u32_e32 v248, 0x30000, v247
	global_store_dwordx4 v248, v[208:211], s[0:1] offset:0
	v_add_u32_e32 v248, 0xb0000, v247
	global_load_dwordx4 v[212:215], v248, s[6:7] offset:0
	v_add_u32_e32 v248, 0x160000, v246
	global_load_dwordx4 v[208:211], v248, s[66:67] offset:0
	s_waitcnt vmcnt(21)
	v_lshlrev_b32_e32 v238, 16, v216
	v_and_b32_e32 v239, 0xffff0000, v216
	v_lshlrev_b32_e32 v242, 16, v220
	v_and_b32_e32 v243, 0xffff0000, v220
	v_pk_fma_f32 v[70:71], v[70:71], v[238:239], v[242:243]
	v_lshlrev_b32_e32 v240, 16, v217
	v_and_b32_e32 v241, 0xffff0000, v217
	v_lshlrev_b32_e32 v244, 16, v221
	v_and_b32_e32 v245, 0xffff0000, v221
	v_pk_fma_f32 v[72:73], v[72:73], v[240:241], v[244:245]
	v_lshlrev_b32_e32 v238, 16, v218
	v_and_b32_e32 v239, 0xffff0000, v218
	v_lshlrev_b32_e32 v242, 16, v222
	v_and_b32_e32 v243, 0xffff0000, v222
	v_pk_fma_f32 v[66:67], v[66:67], v[238:239], v[242:243]
	v_lshlrev_b32_e32 v240, 16, v219
	v_and_b32_e32 v241, 0xffff0000, v219
	v_lshlrev_b32_e32 v244, 16, v223
	v_and_b32_e32 v245, 0xffff0000, v223
	v_pk_fma_f32 v[68:69], v[68:69], v[240:241], v[244:245]
	v_cvt_pk_bf16_f32 v216, v70, v71
	v_cvt_pk_bf16_f32 v217, v72, v73
	v_cvt_pk_bf16_f32 v218, v66, v67
	v_cvt_pk_bf16_f32 v219, v68, v69
	v_add_u32_e32 v248, 0x30000, v247
	global_store_dwordx4 v248, v[216:219], s[0:1] offset:256
	v_add_u32_e32 v248, 0xb0000, v247
	global_load_dwordx4 v[220:223], v248, s[6:7] offset:256
	v_add_u32_e32 v248, 0x160000, v246
	global_load_dwordx4 v[216:219], v248, s[66:67] offset:256
	s_waitcnt vmcnt(21)
; __device__ __forceinline__ u32x4 pack8(const f32x4 a, const f32x4 b) { u32x4 w; w.x = cvt_pk_bf16(a[0], a[1]); w.y = cvt_pk_bf16(a[2], a[3]); w.z = cvt_pk_bf16(b[0], b[1]); w.w = cvt_pk_bf16(b[2], b[3]); return w; }
; __device__ __forceinline__ void unpack8(const u32x4 w, f32x4& a, f32x4& b) { a = (f32x4){bflo(w.x), bfhi(w.x), bflo(w.y), bfhi(w.y)}; b = (f32x4){bflo(w.z), bfhi(w.z), bflo(w.w), bfhi(w.w)}; }
;     __device__ __forceinline__ void operator()(const f32x4 (&acc)[2][2][4][2], const Unit& u, int wr, int wc, int fr, int fq) const {
;         const int row0 = u.pm * BM + wr * 64 + fr, col0 = u.pn * BM + wc * 32 + 8 * fq;
; #pragma unroll
;         for (int ai = 0; ai < 2; ++ai)
; #pragma unroll
;             for (int m = 0; m < 4; ++m) { const int row = row0 + ai * HALF + m * 16;
; #pragma unroll
;                 for (int bj = 0; bj < 2; ++bj) { const int c = col0 + bj * HALF;
;                     f32x4 g0, g1; unpack8(*(const u32x4*)(gates + (size_t)row * 4096 + STAGE * 2048 + c), g0, g1);
;                     f32x4 v0 = acc[ai][bj][m][0] * g0, v1 = acc[ai][bj][m][1] * g1;
;                     if (STAGE == 0) { *(u32x4*)(t1 + (size_t)row * 2048 + c) = pack8(v0, v1); }
;                     else { f32x4 t0, t1v; unpack8(*(const u32x4*)(t1 + (size_t)row * 2048 + c), t0, t1v); *(u32x4*)(g + (size_t)row * 2048 + c) = pack8(v0 + t0, v1 + t1v); } } }
	v_lshlrev_b32_e32 v238, 16, v144
	v_and_b32_e32 v239, 0xffff0000, v144
	v_lshlrev_b32_e32 v242, 16, v156
	v_and_b32_e32 v243, 0xffff0000, v156
	v_pk_fma_f32 v[62:63], v[62:63], v[238:239], v[242:243]
	v_lshlrev_b32_e32 v240, 16, v145
	v_and_b32_e32 v241, 0xffff0000, v145
	v_lshlrev_b32_e32 v244, 16, v157
	v_and_b32_e32 v245, 0xffff0000, v157
	v_pk_fma_f32 v[64:65], v[64:65], v[240:241], v[244:245]
	v_lshlrev_b32_e32 v238, 16, v146
	v_and_b32_e32 v239, 0xffff0000, v146
	v_lshlrev_b32_e32 v242, 16, v158
	v_and_b32_e32 v243, 0xffff0000, v158
	v_pk_fma_f32 v[58:59], v[58:59], v[238:239], v[242:243]
	v_lshlrev_b32_e32 v240, 16, v147
	v_and_b32_e32 v241, 0xffff0000, v147
	v_lshlrev_b32_e32 v244, 16, v159
	v_and_b32_e32 v245, 0xffff0000, v159
	v_pk_fma_f32 v[60:61], v[60:61], v[240:241], v[244:245]
	v_cvt_pk_bf16_f32 v144, v62, v63
	v_cvt_pk_bf16_f32 v145, v64, v65
	v_cvt_pk_bf16_f32 v146, v58, v59
	v_cvt_pk_bf16_f32 v147, v60, v61
	v_add_u32_e32 v248, 0x80000, v247
	global_store_dwordx4 v248, v[144:147], s[0:1] offset:0
	s_waitcnt vmcnt(19)
	v_lshlrev_b32_e32 v238, 16, v160
	v_and_b32_e32 v239, 0xffff0000, v160
	v_lshlrev_b32_e32 v242, 16, v166
	v_and_b32_e32 v243, 0xffff0000, v166
	v_pk_fma_f32 v[54:55], v[54:55], v[238:239], v[242:243]
	v_lshlrev_b32_e32 v240, 16, v161
	v_and_b32_e32 v241, 0xffff0000, v161
	v_lshlrev_b32_e32 v244, 16, v167
	v_and_b32_e32 v245, 0xffff0000, v167
	v_pk_fma_f32 v[56:57], v[56:57], v[240:241], v[244:245]
	v_lshlrev_b32_e32 v238, 16, v162
	v_and_b32_e32 v239, 0xffff0000, v162
	v_lshlrev_b32_e32 v242, 16, v168
	v_and_b32_e32 v243, 0xffff0000, v168
	v_pk_fma_f32 v[50:51], v[50:51], v[238:239], v[242:243]
	v_lshlrev_b32_e32 v240, 16, v163
	v_and_b32_e32 v241, 0xffff0000, v163
	v_lshlrev_b32_e32 v244, 16, v169
	v_and_b32_e32 v245, 0xffff0000, v169
	v_pk_fma_f32 v[52:53], v[52:53], v[240:241], v[244:245]
	v_cvt_pk_bf16_f32 v160, v54, v55
	v_cvt_pk_bf16_f32 v161, v56, v57
	v_cvt_pk_bf16_f32 v162, v50, v51
	v_cvt_pk_bf16_f32 v163, v52, v53
	v_add_u32_e32 v248, 0x80000, v247
	global_store_dwordx4 v248, v[160:163], s[0:1] offset:256
	s_waitcnt vmcnt(17)
	v_lshlrev_b32_e32 v238, 16, v170
	v_and_b32_e32 v239, 0xffff0000, v170
	v_lshlrev_b32_e32 v242, 16, v174
	v_and_b32_e32 v243, 0xffff0000, v174
	v_pk_fma_f32 v[46:47], v[46:47], v[238:239], v[242:243]
	v_lshlrev_b32_e32 v240, 16, v171
	v_and_b32_e32 v241, 0xffff0000, v171
	v_lshlrev_b32_e32 v244, 16, v175
	v_and_b32_e32 v245, 0xffff0000, v175
	v_pk_fma_f32 v[48:49], v[48:49], v[240:241], v[244:245]
	v_lshlrev_b32_e32 v238, 16, v172
	v_and_b32_e32 v239, 0xffff0000, v172
	v_lshlrev_b32_e32 v242, 16, v176
	v_and_b32_e32 v243, 0xffff0000, v176
	v_pk_fma_f32 v[42:43], v[42:43], v[238:239], v[242:243]
	v_lshlrev_b32_e32 v240, 16, v173
	v_and_b32_e32 v241, 0xffff0000, v173
	v_lshlrev_b32_e32 v244, 16, v177
	v_and_b32_e32 v245, 0xffff0000, v177
	v_pk_fma_f32 v[44:45], v[44:45], v[240:241], v[244:245]
	v_cvt_pk_bf16_f32 v170, v46, v47
	v_cvt_pk_bf16_f32 v171, v48, v49
	v_cvt_pk_bf16_f32 v172, v42, v43
	v_cvt_pk_bf16_f32 v173, v44, v45
	v_add_u32_e32 v248, 0x90000, v247
	global_store_dwordx4 v248, v[170:173], s[0:1] offset:0
	s_waitcnt vmcnt(15)
	v_lshlrev_b32_e32 v238, 16, v178
	v_and_b32_e32 v239, 0xffff0000, v178
	v_lshlrev_b32_e32 v242, 16, v182
	v_and_b32_e32 v243, 0xffff0000, v182
	v_pk_fma_f32 v[38:39], v[38:39], v[238:239], v[242:243]
	v_lshlrev_b32_e32 v240, 16, v179
	v_and_b32_e32 v241, 0xffff0000, v179
	v_lshlrev_b32_e32 v244, 16, v183
	v_and_b32_e32 v245, 0xffff0000, v183
	v_pk_fma_f32 v[40:41], v[40:41], v[240:241], v[244:245]
	v_lshlrev_b32_e32 v238, 16, v180
	v_and_b32_e32 v239, 0xffff0000, v180
	v_lshlrev_b32_e32 v242, 16, v184
	v_and_b32_e32 v243, 0xffff0000, v184
	v_pk_fma_f32 v[34:35], v[34:35], v[238:239], v[242:243]
	v_lshlrev_b32_e32 v240, 16, v181
	v_and_b32_e32 v241, 0xffff0000, v181
	v_lshlrev_b32_e32 v244, 16, v185
	v_and_b32_e32 v245, 0xffff0000, v185
	v_pk_fma_f32 v[36:37], v[36:37], v[240:241], v[244:245]
	v_cvt_pk_bf16_f32 v178, v38, v39
	v_cvt_pk_bf16_f32 v179, v40, v41
	v_cvt_pk_bf16_f32 v180, v34, v35
	v_cvt_pk_bf16_f32 v181, v36, v37
	v_add_u32_e32 v248, 0x90000, v247
	global_store_dwordx4 v248, v[178:181], s[0:1] offset:256
	s_waitcnt vmcnt(13)
; __device__ __forceinline__ u32x4 pack8(const f32x4 a, const f32x4 b) { u32x4 w; w.x = cvt_pk_bf16(a[0], a[1]); w.y = cvt_pk_bf16(a[2], a[3]); w.z = cvt_pk_bf16(b[0], b[1]); w.w = cvt_pk_bf16(b[2], b[3]); return w; }
; __device__ __forceinline__ void unpack8(const u32x4 w, f32x4& a, f32x4& b) { a = (f32x4){bflo(w.x), bfhi(w.x), bflo(w.y), bfhi(w.y)}; b = (f32x4){bflo(w.z), bfhi(w.z), bflo(w.w), bfhi(w.w)}; }
;     __device__ __forceinline__ void operator()(const f32x4 (&acc)[2][2][4][2], const Unit& u, int wr, int wc, int fr, int fq) const {
;         const int row0 = u.pm * BM + wr * 64 + fr, col0 = u.pn * BM + wc * 32 + 8 * fq;
; #pragma unroll
;         for (int ai = 0; ai < 2; ++ai)
; #pragma unroll
;             for (int m = 0; m < 4; ++m) { const int row = row0 + ai * HALF + m * 16;
; #pragma unroll
;                 for (int bj = 0; bj < 2; ++bj) { const int c = col0 + bj * HALF;
;                     f32x4 g0, g1; unpack8(*(const u32x4*)(gates + (size_t)row * 4096 + STAGE * 2048 + c), g0, g1);
;                     f32x4 v0 = acc[ai][bj][m][0] * g0, v1 = acc[ai][bj][m][1] * g1;
;                     if (STAGE == 0) { *(u32x4*)(t1 + (size_t)row * 2048 + c) = pack8(v0, v1); }
;                     else { f32x4 t0, t1v; unpack8(*(const u32x4*)(t1 + (size_t)row * 2048 + c), t0, t1v); *(u32x4*)(g + (size_t)row * 2048 + c) = pack8(v0 + t0, v1 + t1v); } } }
	v_lshlrev_b32_e32 v238, 16, v186
	v_and_b32_e32 v239, 0xffff0000, v186
	v_lshlrev_b32_e32 v242, 16, v190
	v_and_b32_e32 v243, 0xffff0000, v190
	v_pk_fma_f32 v[30:31], v[30:31], v[238:239], v[242:243]
	v_lshlrev_b32_e32 v240, 16, v187
	v_and_b32_e32 v241, 0xffff0000, v187
	v_lshlrev_b32_e32 v244, 16, v191
	v_and_b32_e32 v245, 0xffff0000, v191
	v_pk_fma_f32 v[32:33], v[32:33], v[240:241], v[244:245]
	v_lshlrev_b32_e32 v238, 16, v188
	v_and_b32_e32 v239, 0xffff0000, v188
	v_lshlrev_b32_e32 v242, 16, v192
	v_and_b32_e32 v243, 0xffff0000, v192
	v_pk_fma_f32 v[26:27], v[26:27], v[238:239], v[242:243]
	v_lshlrev_b32_e32 v240, 16, v189
	v_and_b32_e32 v241, 0xffff0000, v189
	v_lshlrev_b32_e32 v244, 16, v193
	v_and_b32_e32 v245, 0xffff0000, v193
	v_pk_fma_f32 v[28:29], v[28:29], v[240:241], v[244:245]
	v_cvt_pk_bf16_f32 v186, v30, v31
	v_cvt_pk_bf16_f32 v187, v32, v33
	v_cvt_pk_bf16_f32 v188, v26, v27
	v_cvt_pk_bf16_f32 v189, v28, v29
	v_add_u32_e32 v248, 0xa0000, v247
	global_store_dwordx4 v248, v[186:189], s[0:1] offset:0
	s_waitcnt vmcnt(11)
	v_lshlrev_b32_e32 v238, 16, v200
	v_and_b32_e32 v239, 0xffff0000, v200
	v_lshlrev_b32_e32 v242, 16, v204
	v_and_b32_e32 v243, 0xffff0000, v204
	v_pk_fma_f32 v[22:23], v[22:23], v[238:239], v[242:243]
	v_lshlrev_b32_e32 v240, 16, v201
	v_and_b32_e32 v241, 0xffff0000, v201
	v_lshlrev_b32_e32 v244, 16, v205
	v_and_b32_e32 v245, 0xffff0000, v205
	v_pk_fma_f32 v[24:25], v[24:25], v[240:241], v[244:245]
	v_lshlrev_b32_e32 v238, 16, v202
	v_and_b32_e32 v239, 0xffff0000, v202
	v_lshlrev_b32_e32 v242, 16, v206
	v_and_b32_e32 v243, 0xffff0000, v206
	v_pk_fma_f32 v[18:19], v[18:19], v[238:239], v[242:243]
	v_lshlrev_b32_e32 v240, 16, v203
	v_and_b32_e32 v241, 0xffff0000, v203
	v_lshlrev_b32_e32 v244, 16, v207
	v_and_b32_e32 v245, 0xffff0000, v207
	v_pk_fma_f32 v[20:21], v[20:21], v[240:241], v[244:245]
	v_cvt_pk_bf16_f32 v200, v22, v23
	v_cvt_pk_bf16_f32 v201, v24, v25
	v_cvt_pk_bf16_f32 v202, v18, v19
	v_cvt_pk_bf16_f32 v203, v20, v21
	v_add_u32_e32 v248, 0xa0000, v247
	global_store_dwordx4 v248, v[200:203], s[0:1] offset:256
	s_waitcnt vmcnt(9)
	v_lshlrev_b32_e32 v238, 16, v208
	v_and_b32_e32 v239, 0xffff0000, v208
	v_lshlrev_b32_e32 v242, 16, v212
	v_and_b32_e32 v243, 0xffff0000, v212
	v_pk_fma_f32 v[14:15], v[14:15], v[238:239], v[242:243]
	v_lshlrev_b32_e32 v240, 16, v209
	v_and_b32_e32 v241, 0xffff0000, v209
	v_lshlrev_b32_e32 v244, 16, v213
	v_and_b32_e32 v245, 0xffff0000, v213
	v_pk_fma_f32 v[16:17], v[16:17], v[240:241], v[244:245]
	v_lshlrev_b32_e32 v238, 16, v210
	v_and_b32_e32 v239, 0xffff0000, v210
	v_lshlrev_b32_e32 v242, 16, v214
	v_and_b32_e32 v243, 0xffff0000, v214
	v_pk_fma_f32 v[10:11], v[10:11], v[238:239], v[242:243]
	v_lshlrev_b32_e32 v240, 16, v211
	v_and_b32_e32 v241, 0xffff0000, v211
	v_lshlrev_b32_e32 v244, 16, v215
	v_and_b32_e32 v245, 0xffff0000, v215
	v_pk_fma_f32 v[12:13], v[12:13], v[240:241], v[244:245]
	v_cvt_pk_bf16_f32 v208, v14, v15
	v_cvt_pk_bf16_f32 v209, v16, v17
	v_cvt_pk_bf16_f32 v210, v10, v11
	v_cvt_pk_bf16_f32 v211, v12, v13
	v_add_u32_e32 v248, 0xb0000, v247
	global_store_dwordx4 v248, v[208:211], s[0:1] offset:0
	s_waitcnt vmcnt(7)
	v_lshlrev_b32_e32 v238, 16, v216
	v_and_b32_e32 v239, 0xffff0000, v216
	v_lshlrev_b32_e32 v242, 16, v220
	v_and_b32_e32 v243, 0xffff0000, v220
	v_pk_fma_f32 v[6:7], v[6:7], v[238:239], v[242:243]
	v_lshlrev_b32_e32 v240, 16, v217
	v_and_b32_e32 v241, 0xffff0000, v217
	v_lshlrev_b32_e32 v244, 16, v221
	v_and_b32_e32 v245, 0xffff0000, v221
	v_pk_fma_f32 v[8:9], v[8:9], v[240:241], v[244:245]
	v_lshlrev_b32_e32 v238, 16, v218
	v_and_b32_e32 v239, 0xffff0000, v218
	v_lshlrev_b32_e32 v242, 16, v222
	v_and_b32_e32 v243, 0xffff0000, v222
	v_pk_fma_f32 v[2:3], v[2:3], v[238:239], v[242:243]
	v_lshlrev_b32_e32 v240, 16, v219
	v_and_b32_e32 v241, 0xffff0000, v219
	v_lshlrev_b32_e32 v244, 16, v223
	v_and_b32_e32 v245, 0xffff0000, v223
	v_pk_fma_f32 v[4:5], v[4:5], v[240:241], v[244:245]
	v_cvt_pk_bf16_f32 v216, v6, v7
	v_cvt_pk_bf16_f32 v217, v8, v9
	v_cvt_pk_bf16_f32 v218, v2, v3
	v_cvt_pk_bf16_f32 v219, v4, v5
	v_add_u32_e32 v248, 0xb0000, v247
	global_store_dwordx4 v248, v[216:219], s[0:1] offset:256
	s_cbranch_vccnz .LBB0_934
	s_andn2_b64 vcc, exec, s[14:15]
	s_cbranch_vccnz .LBB0_933
	s_barrier
	s_branch .LBB0_933
